# adds counted first wait in the P8 residual epilogue (row-group 1 loads stay in flight) on top of the P7 static-priority build
# baseline (speedup 1.0000x reference)
;     __device__ __forceinline__ void operator()(const f32x4 (&acc)[2][2][4][2], const Unit& u, int wr, int wc, int fr, int fq) const {
;     ...
;         GAS const float* rb = (GAS const float*)((u.pm < MP / BM) ? r0 : r1);
;         GAS float* Cg = (GAS float*)C; GAS bf16_t* Hg = (GAS bf16_t*)HG; GAS const float* sabg = (GAS const float*)sab; GAS float* ssqg = (GAS float*)ssq;
;         f32x4 gc[2][2]; float rsb[8];
;         if (HG) {
; #pragma unroll
;             for (int bj = 0; bj < 2; ++bj)
; #pragma unroll
;                 for (int n = 0; n < 2; ++n) gc[bj][n] = *(GAS const f32x4*)((GAS const float*)gcol + col0 + bj * HALF + n * 4); }
; #pragma unroll
;         for (int g = 0; g < 8; ++g) rsb[g] = sab ? sabg[2 * (size_t)(row0 + (g >> 2) * HALF + (g & 3) * 16) + 1] : 0.f;
;         f32x4 nx[2][2];
;         { const size_t off = (size_t)row0 * D + col0;
; #pragma unroll
;           for (int bj = 0; bj < 2; ++bj)
; #pragma unroll
;             for (int n = 0; n < 2; ++n) nx[bj][n] = *(GAS const f32x4*)(rb + off + bj * HALF + n * 4); }
; #pragma unroll
;         for (int g = 0; g < 8; ++g) { const int ai = g >> 2, m = g & 3;
;             const int row = row0 + ai * HALF + m * 16; const size_t off = (size_t)row * D + col0;
;             f32x4 cur[2][2];
; #pragma unroll
;             for (int bj = 0; bj < 2; ++bj)
; #pragma unroll
;                 for (int n = 0; n < 2; ++n) cur[bj][n] = nx[bj][n];
;             if (g < 7) { const size_t offn = (size_t)(row0 + ((g + 1) >> 2) * HALF + ((g + 1) & 3) * 16) * D + col0;
; #pragma unroll
;                 for (int bj = 0; bj < 2; ++bj)
; #pragma unroll
;                     for (int n = 0; n < 2; ++n) nx[bj][n] = *(GAS const f32x4*)(rb + offn + bj * HALF + n * 4); }
;             const float rs = sab ? rsqrtf(rsb[g] * (1.f / GW) + EPS) : 1.0f;
;             f32x4 v[2][2]; float ss = 0.f;
; #pragma unroll
;             for (int bj = 0; bj < 2; ++bj)
; #pragma unroll
;                 for (int n = 0; n < 2; ++n) { v[bj][n] = cur[bj][n] + acc[ai][bj][m][n] * rs; *(GAS f32x4*)(Cg + off + bj * HALF + n * 4) = v[bj][n];
;                     ss += (v[bj][n][0] * v[bj][n][0] + v[bj][n][1] * v[bj][n][1]) + (v[bj][n][2] * v[bj][n][2] + v[bj][n][3] * v[bj][n][3]); }
;             if (HG) {
; #pragma unroll
;                 for (int bj = 0; bj < 2; ++bj) { const f32x4 a0 = v[bj][0] * gc[bj][0], a1 = v[bj][1] * gc[bj][1];
.LBB0_1609:
	s_cmp_lt_i32 s81, 64
	v_ashrrev_i32_e32 v211, 31, v210
	s_cselect_b32 s3, s7, 0
	s_cselect_b32 s2, s6, 0
	v_lshlrev_b64 v[146:147], 13, v[210:211]
	v_lshl_add_u64 v[146:147], s[2:3], 0, v[146:147]
	v_lshlrev_b64 v[148:149], 2, v[212:213]
	v_lshl_add_u64 v[146:147], v[146:147], 0, v[148:149]
	v_or_b32_e32 v178, 16, v210
	global_load_dwordx4 v[162:165], v[146:147], off offset:16
	global_load_dwordx4 v[166:169], v[146:147], off
	global_load_dwordx4 v[182:185], v[146:147], off offset:528
	global_load_dwordx4 v[216:219], v[146:147], off offset:512
	v_lshlrev_b64 v[146:147], 11, v[210:211]
	v_ashrrev_i32_e32 v179, 31, v178
	v_lshl_add_u64 v[214:215], s[2:3], 0, v[148:149]
	v_lshl_add_u64 v[180:181], v[146:147], 0, v[212:213]
	v_lshlrev_b64 v[146:147], 13, v[178:179]
	v_lshl_add_u64 v[150:151], v[214:215], 0, v[146:147]
	global_load_dwordx4 v[154:157], v[150:151], off offset:16
	global_load_dwordx4 v[158:161], v[150:151], off
	global_load_dwordx4 v[146:149], v[150:151], off offset:528
	s_nop 0
	global_load_dwordx4 v[150:153], v[150:151], off offset:512
	v_lshl_add_u64 v[236:237], v[180:181], 2, s[48:49]
	s_and_b64 vcc, exec, s[46:47]
	v_xor_b32_e32 v235, 16, v221
	s_waitcnt vmcnt(4)
	v_pk_add_f32 v[172:173], v[124:125], v[164:165]
	v_pk_add_f32 v[176:177], v[128:129], v[168:169]
	v_pk_add_f32 v[174:175], v[126:127], v[166:167]
	v_pk_add_f32 v[170:171], v[122:123], v[162:163]
	v_pk_add_f32 v[164:165], v[112:113], v[218:219]
	v_pk_add_f32 v[162:163], v[110:111], v[216:217]
	v_pk_add_f32 v[168:169], v[104:105], v[184:185]
	v_pk_add_f32 v[166:167], v[102:103], v[182:183]
	global_store_dwordx4 v[236:237], v[174:177], off
	global_store_dwordx4 v[236:237], v[170:173], off offset:16
	global_store_dwordx4 v[236:237], v[162:165], off offset:512
	global_store_dwordx4 v[236:237], v[166:169], off offset:528
	v_and_b32_e32 v236, 64, v221
	v_xor_b32_e32 v237, 32, v221
	s_cbranch_vccnz .LBB0_1613
	v_mul_f32_e32 v182, v175, v175
	v_mul_f32_e32 v183, v177, v177
	v_fmac_f32_e32 v182, v174, v174
	v_fmac_f32_e32 v183, v176, v176
	v_add_f32_e32 v182, v182, v183
	v_mul_f32_e32 v183, v171, v171
	v_mul_f32_e32 v184, v173, v173
	v_fmac_f32_e32 v183, v170, v170
	v_fmac_f32_e32 v184, v172, v172
	v_add_f32_e32 v183, v183, v184
	v_add_f32_e32 v182, v182, v183
	v_mul_f32_e32 v183, v163, v163
	v_mul_f32_e32 v184, v165, v165
	v_fmac_f32_e32 v183, v162, v162
	v_fmac_f32_e32 v184, v164, v164
	v_add_f32_e32 v183, v183, v184
	v_add_f32_e32 v182, v182, v183
	v_mul_f32_e32 v183, v167, v167
	v_mul_f32_e32 v184, v169, v169
	v_fmac_f32_e32 v183, v166, v166
	v_fmac_f32_e32 v184, v168, v168
	v_add_f32_e32 v183, v183, v184
	v_add_f32_e32 v184, v182, v183
	v_lshl_add_u64 v[180:181], v[180:181], 1, s[14:15]
	v_pk_mul_f32 v[176:177], v[144:145], v[176:177]
	v_pk_mul_f32 v[174:175], v[142:143], v[174:175]
	v_pk_mul_f32 v[182:183], v[140:141], v[172:173]
	v_pk_mul_f32 v[172:173], v[138:139], v[170:171]
	v_cvt_pk_bf16_f32 v170, v174, v175
	v_cvt_pk_bf16_f32 v171, v176, v177
	v_pk_mul_f32 v[162:163], v[134:135], v[162:163]
	v_cvt_pk_bf16_f32 v172, v172, v173
	v_cvt_pk_bf16_f32 v173, v182, v183
	global_store_dwordx4 v[180:181], v[170:173], off
	v_pk_mul_f32 v[166:167], v[130:131], v[166:167]
	v_pk_mul_f32 v[168:169], v[132:133], v[168:169]
	v_pk_mul_f32 v[170:171], v[136:137], v[164:165]
	v_add_u32_e32 v165, 64, v236
	v_cmp_lt_i32_e32 vcc, v235, v165
	s_nop 1
	v_cndmask_b32_e32 v164, v221, v235, vcc
	v_lshlrev_b32_e32 v164, 2, v164
	ds_bpermute_b32 v172, v164, v184
	v_cmp_lt_i32_e32 vcc, v237, v165
	v_cvt_pk_bf16_f32 v164, v162, v163
	v_cvt_pk_bf16_f32 v165, v170, v171
	v_cvt_pk_bf16_f32 v166, v166, v167
	s_waitcnt lgkmcnt(0)
	v_add_f32_e32 v162, v184, v172
	v_cvt_pk_bf16_f32 v167, v168, v169
	v_cndmask_b32_e32 v163, v221, v237, vcc
	v_lshlrev_b32_e32 v163, 2, v163
	ds_bpermute_b32 v163, v163, v162
	global_store_dwordx4 v[180:181], v[164:167], off offset:256
	s_and_saveexec_b64 s[22:23], s[42:43]
	s_cbranch_execz .LBB0_1612
	v_lshl_add_u64 v[164:165], v[210:211], 2, s[18:19]
	s_waitcnt lgkmcnt(0)
	v_add_f32_e32 v162, v162, v163
	global_atomic_add_f32 v[164:165], v162, off

; __device__ __forceinline__ unsigned pk2(float lo, float hi) { unsigned r; asm volatile("v_cvt_pk_bf16_f32 %0, %1, %2" : "=v"(r) : "v"(lo), "v"(hi)); return r; }
; #define GAS __attribute__((address_space(1)))
;     __device__ __forceinline__ void operator()(const f32x4 (&acc)[2][2][4][2], const Unit& u, int wr, int wc, int fr, int fq) const {
;     ...
;         for (int g = 0; g < 8; ++g) { const int ai = g >> 2, m = g & 3;
;             const int row = row0 + ai * HALF + m * 16; const size_t off = (size_t)row * D + col0;
;             f32x4 cur[2][2];
; #pragma unroll
;             for (int bj = 0; bj < 2; ++bj)
; #pragma unroll
;                 for (int n = 0; n < 2; ++n) cur[bj][n] = nx[bj][n];
;             if (g < 7) { const size_t offn = (size_t)(row0 + ((g + 1) >> 2) * HALF + ((g + 1) & 3) * 16) * D + col0;
; #pragma unroll
;                 for (int bj = 0; bj < 2; ++bj)
; #pragma unroll
;                     for (int n = 0; n < 2; ++n) nx[bj][n] = *(GAS const f32x4*)(rb + offn + bj * HALF + n * 4); }
;             const float rs = sab ? rsqrtf(rsb[g] * (1.f / GW) + EPS) : 1.0f;
;             f32x4 v[2][2]; float ss = 0.f;
; #pragma unroll
;             for (int bj = 0; bj < 2; ++bj)
; #pragma unroll
;                 for (int n = 0; n < 2; ++n) { v[bj][n] = cur[bj][n] + acc[ai][bj][m][n] * rs; *(GAS f32x4*)(Cg + off + bj * HALF + n * 4) = v[bj][n];
;                     ss += (v[bj][n][0] * v[bj][n][0] + v[bj][n][1] * v[bj][n][1]) + (v[bj][n][2] * v[bj][n][2] + v[bj][n][3] * v[bj][n][3]); }
;             if (HG) {
; #pragma unroll
;                 for (int bj = 0; bj < 2; ++bj) { const f32x4 a0 = v[bj][0] * gc[bj][0], a1 = v[bj][1] * gc[bj][1];
;                     u32x4 w; w.x = pk2(a0[0], a0[1]); w.y = pk2(a0[2], a0[3]); w.z = pk2(a1[0], a1[1]); w.w = pk2(a1[2], a1[3]);
;                     *(GAS u32x4*)(Hg + off + bj * HALF) = w; }
;                 ss += __shfl_xor(ss, 16); ss += __shfl_xor(ss, 32);
;                 if (fq == 0) __builtin_amdgcn_global_atomic_fadd_f32(ssqg + row, ss);
.LBB0_1613:
	v_or_b32_e32 v216, 32, v210
	v_ashrrev_i32_e32 v217, 31, v216
	s_waitcnt lgkmcnt(0)
	v_lshlrev_b64 v[162:163], 13, v[216:217]
	v_lshl_add_u64 v[166:167], v[214:215], 0, v[162:163]
	global_load_dwordx4 v[170:173], v[166:167], off offset:16
	global_load_dwordx4 v[182:185], v[166:167], off
	global_load_dwordx4 v[162:165], v[166:167], off offset:528
	s_nop 0
	global_load_dwordx4 v[166:169], v[166:167], off offset:512
	v_lshlrev_b64 v[174:175], 11, v[178:179]
	v_lshl_add_u64 v[174:175], v[174:175], 0, v[212:213]
	v_lshl_add_u64 v[176:177], v[174:175], 2, s[48:49]
	s_waitcnt vmcnt(8)
	v_pk_add_f32 v[160:161], v[120:121], v[160:161]
	v_pk_add_f32 v[158:159], v[118:119], v[158:159]
	v_pk_add_f32 v[156:157], v[116:117], v[156:157]
	v_pk_add_f32 v[154:155], v[114:115], v[154:155]
	v_pk_add_f32 v[152:153], v[96:97], v[152:153]
	v_pk_add_f32 v[150:151], v[94:95], v[150:151]
	v_pk_add_f32 v[148:149], v[88:89], v[148:149]
	v_pk_add_f32 v[146:147], v[86:87], v[146:147]
	s_and_b64 vcc, exec, s[46:47]
	global_store_dwordx4 v[176:177], v[158:161], off
	global_store_dwordx4 v[176:177], v[154:157], off offset:16
	global_store_dwordx4 v[176:177], v[150:153], off offset:512
	global_store_dwordx4 v[176:177], v[146:149], off offset:528
	s_cbranch_vccnz .LBB0_1617
	v_mul_f32_e32 v176, v159, v159
	v_mul_f32_e32 v177, v161, v161
	v_fmac_f32_e32 v176, v158, v158
	v_fmac_f32_e32 v177, v160, v160
	v_add_f32_e32 v176, v176, v177
	v_mul_f32_e32 v177, v155, v155
	v_mul_f32_e32 v178, v157, v157
	v_fmac_f32_e32 v177, v154, v154
	v_fmac_f32_e32 v178, v156, v156
	v_add_f32_e32 v177, v177, v178
	v_add_f32_e32 v176, v176, v177
	v_mul_f32_e32 v177, v151, v151
	v_mul_f32_e32 v178, v153, v153
	v_fmac_f32_e32 v177, v150, v150
	v_fmac_f32_e32 v178, v152, v152
	v_add_f32_e32 v177, v177, v178
	v_add_f32_e32 v176, v176, v177
	v_mul_f32_e32 v177, v147, v147
	v_mul_f32_e32 v178, v149, v149
	v_fmac_f32_e32 v177, v146, v146
	v_fmac_f32_e32 v178, v148, v148
	v_add_f32_e32 v177, v177, v178
	v_pk_mul_f32 v[158:159], v[142:143], v[158:159]
	v_add_f32_e32 v178, v176, v177
	v_pk_mul_f32 v[176:177], v[140:141], v[156:157]
	v_pk_mul_f32 v[156:157], v[138:139], v[154:155]
	v_cvt_pk_bf16_f32 v154, v158, v159
	v_add_u32_e32 v158, 64, v236
	v_lshl_add_u64 v[174:175], v[174:175], 1, s[14:15]
	v_cmp_lt_i32_e32 vcc, v235, v158
	v_pk_mul_f32 v[160:161], v[144:145], v[160:161]
	v_pk_mul_f32 v[150:151], v[134:135], v[150:151]
	v_cvt_pk_bf16_f32 v155, v160, v161
	v_cvt_pk_bf16_f32 v156, v156, v157
	v_cvt_pk_bf16_f32 v157, v176, v177
	global_store_dwordx4 v[174:175], v[154:157], off
	v_pk_mul_f32 v[152:153], v[136:137], v[152:153]
	s_nop 0
	v_cndmask_b32_e32 v154, v221, v235, vcc
	v_lshlrev_b32_e32 v154, 2, v154
	ds_bpermute_b32 v159, v154, v178
	v_cmp_lt_i32_e32 vcc, v237, v158
	v_pk_mul_f32 v[156:157], v[130:131], v[146:147]
	v_pk_mul_f32 v[154:155], v[132:133], v[148:149]
	v_cndmask_b32_e32 v147, v221, v237, vcc
	s_waitcnt lgkmcnt(0)
	v_add_f32_e32 v146, v178, v159
	v_lshlrev_b32_e32 v147, 2, v147
	ds_bpermute_b32 v147, v147, v146
	v_cvt_pk_bf16_f32 v148, v150, v151
	v_cvt_pk_bf16_f32 v149, v152, v153
	v_cvt_pk_bf16_f32 v150, v156, v157
	v_cvt_pk_bf16_f32 v151, v154, v155
	global_store_dwordx4 v[174:175], v[148:151], off offset:256
	s_and_saveexec_b64 s[22:23], s[42:43]
	s_cbranch_execz .LBB0_1616
	v_lshl_add_u64 v[148:149], v[210:211], 2, s[18:19]
	s_waitcnt lgkmcnt(0)
	v_add_f32_e32 v146, v146, v147
	global_atomic_add_f32 v[148:149], v146, off offset:64
